# SEL loop: next-block scalar search moved before the staging barrier
# speedup vs baseline: 1.1072x; 1.0124x over previous
.LBB0_1622:
	s_cmpk_gt_u32 s94, 0xfe
	s_movk_i32 s95, 0x100
	s_waitcnt vmcnt(4)
	ds_write_b128 v249, v[128:131]
	ds_write_b128 v250, v[124:127] offset:4096
	ds_write_b128 v249, v[120:123] offset:8192
	ds_write_b128 v250, v[116:119] offset:12288
	s_waitcnt vmcnt(0)
	ds_write_b128 v251, v[144:147] offset:16384
	ds_write_b128 v251, v[140:143] offset:20480
	ds_write_b128 v251, v[136:139] offset:24576
	ds_write_b128 v251, v[132:135] offset:28672
	s_cbranch_scc1 .LBB0_1632
	s_add_i32 s22, s94, 1
	s_cmp_gt_u32 s94, 62
	s_cselect_b64 s[18:19], -1, 0
	s_lshl_b64 s[0:1], -1, s22
	s_and_b64 s[20:21], s[0:1], s[10:11]
	s_cmp_eq_u64 s[20:21], 0
	s_cselect_b64 s[24:25], -1, 0
	s_or_b64 s[24:25], s[18:19], s[24:25]
	s_mov_b64 s[18:19], -1
	s_and_b64 vcc, exec, s[24:25]
	s_cbranch_vccnz .LBB0_1625
	s_ff1_i32_b64 s95, s[20:21]
	s_mov_b64 s[18:19], 0

.LBB0_1632:
	s_waitcnt lgkmcnt(0)
	s_barrier
	s_min_u32 s0, s95, 0xff
	s_lshl_b32 s0, s0, 2
	s_add_i32 s18, s0, 0x10200
	s_cmp_gt_u32 s95, s86
	s_cselect_b64 s[78:79], -1, 0
	s_and_b64 s[0:1], s[78:79], exec
	s_cselect_b32 s0, s94, s95
	s_lshl_b32 s56, s0, 14
	v_lshl_add_u64 v[0:1], v[164:165], 0, s[56:57]
	v_lshl_add_u64 v[246:247], v[0:1], 0, s[98:99]
	global_load_dwordx4 v[116:119], v[246:247], off
	global_load_dwordx4 v[120:123], v[246:247], off offset:-4096
	global_load_dwordx4 v[124:127], v[0:1], off
	global_load_dwordx4 v[128:131], v[0:1], off offset:-4096
	v_lshl_add_u64 v[0:1], v[166:167], 0, s[56:57]
	v_lshl_add_u64 v[244:245], v[0:1], 0, s[98:99]
	global_load_dwordx4 v[132:135], v[244:245], off
	global_load_dwordx4 v[136:139], v[244:245], off offset:-4096
	global_load_dwordx4 v[140:143], v[0:1], off
	global_load_dwordx4 v[144:147], v[0:1], off offset:-4096
	v_mov_b32_e32 v0, s18
	ds_read_b32 v19, v0
	v_readfirstlane_b32 s0, v2
	s_nop 1
	v_ashrrev_i32_e64 v207, v185, s0
	v_and_b32_e32 v0, 15, v207
	v_cmp_ne_u32_e32 vcc, 0, v0
	s_and_saveexec_b64 s[80:81], vcc
	s_cbranch_execz .LBB0_1642
	ds_read_b128 v[0:3], v187
	ds_read_b128 v[4:7], v188
	ds_read_b128 v[8:11], v189
	ds_read_b128 v[12:15], v190
	ds_read_b128 v[148:151], v191
	ds_read_b128 v[152:155], v192
	ds_read_b128 v[156:159], v193
	ds_read_b128 v[208:211], v194
	s_waitcnt lgkmcnt(7)
	v_mfma_f32_16x16x32_bf16 v[0:3], v[0:3], v[20:23], 0
	s_waitcnt lgkmcnt(6)
	v_mfma_f32_16x16x32_bf16 v[4:7], v[4:7], v[20:23], 0
	s_waitcnt lgkmcnt(5)
	v_mfma_f32_16x16x32_bf16 v[0:3], v[8:11], v[24:27], v[0:3]
	s_waitcnt lgkmcnt(4)
	v_mfma_f32_16x16x32_bf16 v[4:7], v[12:15], v[24:27], v[4:7]
	s_waitcnt lgkmcnt(3)
	v_mfma_f32_16x16x32_bf16 v[0:3], v[148:151], v[28:31], v[0:3]
	s_waitcnt lgkmcnt(2)
	v_mfma_f32_16x16x32_bf16 v[4:7], v[152:155], v[28:31], v[4:7]
	s_waitcnt lgkmcnt(1)
	v_mfma_f32_16x16x32_bf16 v[160:163], v[156:159], v[32:35], v[0:3]
	s_waitcnt lgkmcnt(0)
	v_mfma_f32_16x16x32_bf16 v[156:159], v[208:211], v[32:35], v[4:7]
	s_nop 1
	v_and_b32_e32 v0, v207, v186
	v_cmp_ne_u32_e64 s[82:83], 0, v0
	ds_read_b128 v[0:3], v187 offset:8192
	ds_read_b128 v[4:7], v195
	ds_read_b128 v[8:11], v189 offset:8192
	ds_read_b128 v[12:15], v196
	ds_read_b128 v[148:151], v191 offset:8192
	ds_read_b128 v[152:155], v197
	ds_read_b128 v[208:211], v193 offset:8192
	ds_read_b128 v[212:215], v198
	s_waitcnt lgkmcnt(7)
	v_mfma_f32_16x16x32_bf16 v[0:3], v[0:3], v[20:23], 0
	s_waitcnt lgkmcnt(6)
	v_mfma_f32_16x16x32_bf16 v[4:7], v[4:7], v[20:23], 0
	s_waitcnt lgkmcnt(5)
	v_mfma_f32_16x16x32_bf16 v[0:3], v[8:11], v[24:27], v[0:3]
	s_waitcnt lgkmcnt(4)
	v_mfma_f32_16x16x32_bf16 v[4:7], v[12:15], v[24:27], v[4:7]
	s_waitcnt lgkmcnt(3)
	v_mfma_f32_16x16x32_bf16 v[0:3], v[148:151], v[28:31], v[0:3]
	s_waitcnt lgkmcnt(2)
	v_mfma_f32_16x16x32_bf16 v[4:7], v[152:155], v[28:31], v[4:7]
	s_waitcnt lgkmcnt(1)
	v_mfma_f32_16x16x32_bf16 v[152:155], v[208:211], v[32:35], v[0:3]
	s_waitcnt lgkmcnt(0)
	v_mfma_f32_16x16x32_bf16 v[148:151], v[212:215], v[32:35], v[4:7]
	s_lshl_b32 s33, s94, 6
	s_or_b32 s0, s33, 63
	v_cmp_le_i32_e32 vcc, s0, v199
	s_and_saveexec_b64 s[0:1], vcc
	s_xor_b64 s[0:1], exec, s[0:1]
	s_or_saveexec_b64 s[26:27], s[0:1]
	s_mov_b64 s[0:1], s[82:83]
	s_mov_b64 s[18:19], s[82:83]
	s_mov_b64 s[20:21], s[82:83]
	s_mov_b64 s[22:23], s[82:83]
	s_mov_b64 s[24:25], s[82:83]
	s_mov_b64 s[28:29], s[82:83]
	s_mov_b64 s[30:31], s[82:83]
	s_mov_b64 s[34:35], s[82:83]
	s_mov_b64 s[36:37], s[82:83]
	s_mov_b64 s[38:39], s[82:83]
	s_mov_b64 s[40:41], s[82:83]
	s_mov_b64 s[42:43], s[82:83]
	s_mov_b64 s[44:45], s[82:83]
	s_mov_b64 s[46:47], s[82:83]
	s_mov_b64 s[48:49], s[82:83]
	s_mov_b64 s[50:51], s[82:83]
	s_mov_b64 s[84:85], s[82:83]
	s_xor_b64 exec, exec, s[26:27]
	s_cbranch_execz .LBB0_1635
	v_cndmask_b32_e64 v1, 0, -1, s[82:83]
	v_or_b32_e32 v2, s33, v201
	v_cndmask_b32_e64 v0, -1, v200, s[82:83]
	v_cmp_gt_i32_e64 s[0:1], v2, v1
	v_or_b32_e32 v1, 2, v2
	v_cmp_le_i32_e64 s[20:21], v1, v0
	v_or_b32_e32 v1, 3, v2
	v_cmp_le_i32_e64 s[22:23], v1, v0
	v_or_b32_e32 v1, 4, v2
	v_cmp_le_i32_e64 s[24:25], v1, v0
	v_or_b32_e32 v1, 5, v2
	v_cmp_le_i32_e64 s[28:29], v1, v0
	v_or_b32_e32 v1, 6, v2
	v_cmp_le_i32_e64 s[30:31], v1, v0
	v_or_b32_e32 v1, 7, v2
	v_cmp_le_i32_e64 s[34:35], v1, v0
	v_or_b32_e32 v1, 32, v2
	v_cmp_le_i32_e64 s[36:37], v1, v0
	v_cmp_lt_i32_e64 s[38:39], v1, v0
	v_or_b32_e32 v1, 34, v2
	v_cmp_le_i32_e64 s[40:41], v1, v0
	v_or_b32_e32 v1, 35, v2
	v_cmp_le_i32_e64 s[42:43], v1, v0
	v_or_b32_e32 v1, 36, v2
	v_cmp_le_i32_e64 s[44:45], v1, v0
	v_or_b32_e32 v1, 37, v2
	v_cmp_le_i32_e64 s[46:47], v1, v0
	v_or_b32_e32 v1, 38, v2
	v_cmp_le_i32_e64 s[18:19], v2, v0
	v_cmp_le_i32_e64 s[48:49], v1, v0
	v_or_b32_e32 v1, 39, v2
	s_and_b64 s[0:1], s[0:1], s[18:19]
	v_cmp_lt_i32_e64 s[18:19], v2, v0
	v_cmp_le_i32_e64 s[50:51], v1, v0
	v_cndmask_b32_e64 v160, v169, v160, s[0:1]
	v_cndmask_b32_e64 v161, v169, v161, s[18:19]
	v_cndmask_b32_e64 v162, v169, v162, s[20:21]
	v_cndmask_b32_e64 v163, v169, v163, s[22:23]
	v_cndmask_b32_e64 v156, v169, v156, s[24:25]
	v_cndmask_b32_e64 v157, v169, v157, s[28:29]
	v_cndmask_b32_e64 v158, v169, v158, s[30:31]
	v_cndmask_b32_e64 v159, v169, v159, s[34:35]
	v_cndmask_b32_e64 v152, v169, v152, s[36:37]
	v_cndmask_b32_e64 v153, v169, v153, s[38:39]
	v_cndmask_b32_e64 v154, v169, v154, s[40:41]
	v_cndmask_b32_e64 v155, v169, v155, s[42:43]
	v_cndmask_b32_e64 v148, v169, v148, s[44:45]
	v_cndmask_b32_e64 v149, v169, v149, s[46:47]
	v_cndmask_b32_e64 v150, v169, v150, s[48:49]
	v_cndmask_b32_e64 v151, v169, v151, s[50:51]
	s_andn2_b64 s[54:55], s[82:83], exec
	s_and_b64 s[50:51], s[50:51], exec
	s_and_b64 s[48:49], s[48:49], exec
	s_and_b64 s[46:47], s[46:47], exec
	s_and_b64 s[44:45], s[44:45], exec
	s_and_b64 s[42:43], s[42:43], exec
	s_and_b64 s[40:41], s[40:41], exec
	s_and_b64 s[38:39], s[38:39], exec
	s_and_b64 s[36:37], s[36:37], exec
	s_and_b64 s[34:35], s[34:35], exec
	s_and_b64 s[30:31], s[30:31], exec
	s_and_b64 s[28:29], s[28:29], exec
	s_and_b64 s[24:25], s[24:25], exec
	s_and_b64 s[22:23], s[22:23], exec
	s_and_b64 s[20:21], s[20:21], exec
	s_and_b64 s[18:19], s[18:19], exec
	s_and_b64 s[0:1], s[0:1], exec
	s_or_b64 s[84:85], s[82:83], exec
	s_or_b64 s[50:51], s[54:55], s[50:51]
	s_or_b64 s[48:49], s[54:55], s[48:49]
	s_or_b64 s[46:47], s[54:55], s[46:47]
	s_or_b64 s[44:45], s[54:55], s[44:45]
	s_or_b64 s[42:43], s[54:55], s[42:43]
	s_or_b64 s[40:41], s[54:55], s[40:41]
	s_or_b64 s[38:39], s[54:55], s[38:39]
	s_or_b64 s[36:37], s[54:55], s[36:37]
	s_or_b64 s[34:35], s[54:55], s[34:35]
	s_or_b64 s[30:31], s[54:55], s[30:31]
	s_or_b64 s[28:29], s[54:55], s[28:29]
	s_or_b64 s[24:25], s[54:55], s[24:25]
	s_or_b64 s[22:23], s[54:55], s[22:23]
	s_or_b64 s[20:21], s[54:55], s[20:21]
	s_or_b64 s[18:19], s[54:55], s[18:19]
	s_or_b64 s[0:1], s[54:55], s[0:1]
